# deferred transposes rebalanced: phase1 tiles [832,2368), phase3 tiles [2368,3392), phase 0 keeps [0,832)+[3392,5952)
# baseline (speedup 1.0000x reference)
.LBB0_17:
	s_load_dwordx16 s[4:19], s[0:1], 0x40
	s_cmp_lt_i32 s24, 1
	s_waitcnt lgkmcnt(0)
	v_writelane_b32 v230, s4, 0
	s_nop 1
	v_writelane_b32 v230, s5, 1
	v_writelane_b32 v230, s6, 2
	v_writelane_b32 v230, s7, 3
	v_writelane_b32 v230, s8, 4
	v_writelane_b32 v230, s9, 5
	v_writelane_b32 v230, s10, 6
	v_writelane_b32 v230, s11, 7
	v_writelane_b32 v230, s12, 8
	v_writelane_b32 v230, s13, 9
	v_writelane_b32 v230, s14, 10
	v_writelane_b32 v230, s15, 11
	v_writelane_b32 v230, s16, 12
	v_writelane_b32 v230, s17, 13
	v_writelane_b32 v230, s18, 14
	v_writelane_b32 v230, s19, 15
	s_cselect_b64 s[4:5], -1, 0
	s_cmp_gt_i32 s25, 0
	s_cselect_b64 s[6:7], -1, 0
	s_and_b64 s[4:5], s[4:5], s[6:7]
	s_andn2_b64 vcc, exec, s[4:5]
	s_cbranch_vccnz .LBB0_147
	s_lshl_b32 s3, s2, 1
	s_cmpk_gt_i32 s3, 0xd3f
	s_cbranch_scc1 .LBB0_75
	v_lshlrev_b32_e32 v0, 3, v129
	s_load_dword s4, s[0:1], 0x148
	v_lshrrev_b32_e32 v14, 8, v129
	v_and_b32_e32 v0, 56, v0
	v_bfe_u32 v18, v129, 3, 5
	v_lshl_add_u32 v2, v14, 15, 0
	v_and_b32_e32 v15, 63, v129
	v_and_b32_e32 v3, 16, v129
	v_mul_u32_u24_e32 v5, 0x104, v0
	v_lshlrev_b32_e32 v6, 2, v18
	v_bfe_u32 v16, v129, 6, 2
	v_lshl_add_u32 v4, v15, 2, v2
	v_add3_u32 v19, v2, v5, v6
	v_mov_b32_e32 v2, s57
	v_mov_b32_e32 v6, s55
	v_cmp_eq_u32_e32 vcc, 0, v3
	v_mul_u32_u24_e32 v5, 0x104, v16
	v_and_b32_e32 v17, 15, v129
	v_cndmask_b32_e32 v3, v2, v6, vcc
	v_mov_b32_e32 v2, s56
	v_mov_b32_e32 v6, s54
	v_mov_b32_e32 v1, 0
	s_waitcnt lgkmcnt(0)
	s_lshl_b32 s16, s4, 1
	v_or_b32_e32 v20, 32, v18
	v_cndmask_b32_e32 v2, v2, v6, vcc
	v_add_u32_e32 v21, v4, v5
	v_lshlrev_b32_e32 v0, 1, v0
	s_branch .LBB0_21
.LBB0_20:
	s_or_b64 exec, exec, s[4:5]
	s_waitcnt vmcnt(0)
	ds_write_b32 v21, v12
	ds_write_b32 v21, v11 offset:1040
	ds_write_b32 v21, v26 offset:2080
	ds_write_b32 v21, v25 offset:3120
	ds_write_b32 v21, v28 offset:4160
	ds_write_b32 v21, v27 offset:5200
	ds_write_b32 v21, v30 offset:6240
	ds_write_b32 v21, v29 offset:7280
	ds_write_b32 v21, v32 offset:8320
	ds_write_b32 v21, v31 offset:9360
	ds_write_b32 v21, v34 offset:10400
	ds_write_b32 v21, v33 offset:11440
	ds_write_b32 v21, v36 offset:12480
	ds_write_b32 v21, v35 offset:13520
	ds_write_b32 v21, v38 offset:14560
	ds_write_b32 v21, v37 offset:15600
	v_ashrrev_i32_e32 v11, 31, v10
	s_waitcnt lgkmcnt(0)
	s_barrier
	v_lshl_add_u64 v[4:5], v[10:11], 1, v[4:5]
	ds_read2_b32 v[8:9], v19 offset1:32
	ds_read2_b32 v[10:11], v19 offset0:65 offset1:97
	ds_read2_b32 v[12:13], v19 offset0:130 offset1:162
	ds_read2_b32 v[24:25], v19 offset0:195 offset1:227
	v_add_u32_e32 v6, 0x400, v19
	ds_read2_b32 v[26:27], v6 offset0:4 offset1:36
	ds_read2_b32 v[28:29], v6 offset0:69 offset1:101
	ds_read2_b32 v[30:31], v6 offset0:134 offset1:166
	ds_read2_b32 v[32:33], v6 offset0:199 offset1:231
	v_lshl_add_u64 v[34:35], v[4:5], 0, v[0:1]
	s_waitcnt lgkmcnt(6)
	v_cvt_pk_bf16_f32 v4, v8, v10
	v_or_b32_e32 v8, v23, v18
	v_ashrrev_i32_e32 v10, 31, v23
	v_mul_lo_u32 v10, v10, v22
	v_mad_u64_u32 v[36:37], s[4:5], v8, v22, 0
	v_add_u32_e32 v37, v37, v10
	s_waitcnt lgkmcnt(4)
	v_cvt_pk_bf16_f32 v5, v12, v24
	s_waitcnt lgkmcnt(2)
	v_cvt_pk_bf16_f32 v6, v26, v28
	s_waitcnt lgkmcnt(0)
	v_cvt_pk_bf16_f32 v7, v30, v32
	v_lshl_add_u64 v[36:37], v[36:37], 1, v[34:35]
	v_or_b32_e32 v8, v23, v20
	global_store_dwordx4 v[36:37], v[4:7], off
	s_add_i32 s3, s3, s16
	s_cmpk_lt_i32 s3, 0xd40
	v_cvt_pk_bf16_f32 v4, v9, v11
	v_mad_u64_u32 v[8:9], s[4:5], v8, v22, 0
	v_add_u32_e32 v9, v9, v10
	v_cvt_pk_bf16_f32 v5, v13, v25
	v_cvt_pk_bf16_f32 v6, v27, v29
	v_cvt_pk_bf16_f32 v7, v31, v33
	v_lshl_add_u64 v[8:9], v[8:9], 1, v[34:35]
	global_store_dwordx4 v[8:9], v[4:7], off
	s_cbranch_scc0 .LBB0_75
.LBB0_21:
	s_load_dwordx16 s[68:83], s[0:1], 0x40
	v_add_u32_e32 v24, s3, v14
	v_add_u32_e32 v25, 0xa00, v24
	v_cmp_lt_i32_e32 vcc, 0x33f, v24
	s_nop 1
	v_cndmask_b32_e32 v24, v24, v25, vcc
	s_movk_i32 s4, 0x33f
	v_cmp_lt_i32_e32 vcc, s4, v24
	v_mov_b64_e32 v[6:7], 0xc10
	v_mov_b32_e32 v22, 0x400
	v_mov_b32_e32 v25, 0xc10
	v_mov_b64_e32 v[4:5], s[60:61]
	s_waitcnt lgkmcnt(0)
	v_mov_b64_e32 v[10:11], s[74:75]
	s_mov_b64 s[6:7], -1
	s_and_saveexec_b64 s[4:5], vcc
	s_cbranch_execz .LBB0_39
	s_load_dwordx16 s[68:83], s[0:1], 0x40
	s_movk_i32 s6, 0x43f
	v_cmp_lt_u32_e32 vcc, s6, v24
	v_mov_b64_e32 v[4:5], s[62:63]
	s_waitcnt lgkmcnt(0)
	v_mov_b64_e32 v[10:11], s[82:83]
	s_and_saveexec_b64 s[8:9], vcc
	s_xor_b64 s[8:9], exec, s[8:9]
	s_cbranch_execz .LBB0_36
	s_movk_i32 s6, 0xc3f
	v_cmp_lt_u32_e32 vcc, s6, v24
	s_and_saveexec_b64 s[10:11], vcc
	s_xor_b64 s[10:11], exec, s[10:11]
	s_cbranch_execz .LBB0_33
	s_movk_i32 s6, 0x143f
	v_cmp_lt_u32_e32 vcc, s6, v24
	s_and_saveexec_b64 s[12:13], vcc
	s_xor_b64 s[12:13], exec, s[12:13]
	s_cbranch_execz .LBB0_30
	s_load_dwordx16 s[68:83], s[0:1], 0x80
	s_movk_i32 s6, 0x153f
	v_cmp_lt_u32_e32 vcc, s6, v24
	v_mov_b64_e32 v[4:5], s[36:37]
	s_waitcnt lgkmcnt(0)
	v_mov_b64_e32 v[10:11], s[68:69]
	s_and_saveexec_b64 s[6:7], vcc
	s_xor_b64 s[6:7], exec, s[6:7]
	v_add_u32_e32 v24, 0xffffeac0, v24
	v_mov_b64_e32 v[10:11], s[54:55]
	v_mov_b64_e32 v[4:5], s[38:39]
	s_or_saveexec_b64 s[14:15], s[6:7]
	s_mov_b64 s[6:7], 0
	v_mov_b32_e32 v25, 0x800
	s_xor_b64 exec, exec, s[14:15]
	s_mov_b64 s[6:7], exec
	v_add_u32_e32 v24, 0xffffebc0, v24
	v_mov_b32_e32 v25, 0x400
	s_or_b64 exec, exec, s[14:15]

.LBB0_165:
	s_cmp_lt_u32 s2, 64
	s_cbranch_scc1 .Ltr1_skip
	s_sub_u32 s3, s2, 64
	s_lshl_b32 s3, s3, 1
	s_addk_i32 s3, 0x340
	s_cmpk_gt_i32 s3, 0x93f
	s_cbranch_scc1 .Ltr1_75
	s_load_dwordx4 s[84:87], s[0:1], 0x100
	s_load_dwordx4 s[88:91], s[0:1], 0xc8
	s_waitcnt lgkmcnt(0)
	s_barrier
	v_lshlrev_b32_e32 v0, 3, v129
	v_lshrrev_b32_e32 v14, 8, v129
	v_and_b32_e32 v0, 56, v0
	v_bfe_u32 v18, v129, 3, 5
	v_lshl_add_u32 v2, v14, 15, 0
	v_and_b32_e32 v15, 63, v129
	v_and_b32_e32 v3, 16, v129
	v_mul_u32_u24_e32 v5, 0x104, v0
	v_lshlrev_b32_e32 v6, 2, v18
	v_bfe_u32 v16, v129, 6, 2
	v_lshl_add_u32 v4, v15, 2, v2
	v_add3_u32 v19, v2, v5, v6
	v_mov_b32_e32 v2, s91
	v_mov_b32_e32 v6, s89
	v_cmp_eq_u32_e32 vcc, 0, v3
	v_mul_u32_u24_e32 v5, 0x104, v16
	v_and_b32_e32 v17, 15, v129
	v_cndmask_b32_e32 v3, v2, v6, vcc
	v_mov_b32_e32 v2, s90
	v_mov_b32_e32 v6, s88
	v_mov_b32_e32 v1, 0
	s_waitcnt lgkmcnt(0)
	s_movk_i32 s16, 0x180
	v_or_b32_e32 v20, 32, v18
	v_cndmask_b32_e32 v2, v2, v6, vcc
	v_add_u32_e32 v21, v4, v5
	v_lshlrev_b32_e32 v0, 1, v0
	s_branch .Ltr1_21
.Ltr1_20:
	s_or_b64 exec, exec, s[4:5]
	s_waitcnt vmcnt(0)
	ds_write_b32 v21, v12
	ds_write_b32 v21, v11 offset:1040
	ds_write_b32 v21, v26 offset:2080
	ds_write_b32 v21, v25 offset:3120
	ds_write_b32 v21, v28 offset:4160
	ds_write_b32 v21, v27 offset:5200
	ds_write_b32 v21, v30 offset:6240
	ds_write_b32 v21, v29 offset:7280
	ds_write_b32 v21, v32 offset:8320
	ds_write_b32 v21, v31 offset:9360
	ds_write_b32 v21, v34 offset:10400
	ds_write_b32 v21, v33 offset:11440
	ds_write_b32 v21, v36 offset:12480
	ds_write_b32 v21, v35 offset:13520
	ds_write_b32 v21, v38 offset:14560
	ds_write_b32 v21, v37 offset:15600
	v_ashrrev_i32_e32 v11, 31, v10
	s_waitcnt lgkmcnt(0)
	s_barrier
	v_lshl_add_u64 v[4:5], v[10:11], 1, v[4:5]
	ds_read2_b32 v[8:9], v19 offset1:32
	ds_read2_b32 v[10:11], v19 offset0:65 offset1:97
	ds_read2_b32 v[12:13], v19 offset0:130 offset1:162
	ds_read2_b32 v[24:25], v19 offset0:195 offset1:227
	v_add_u32_e32 v6, 0x400, v19
	ds_read2_b32 v[26:27], v6 offset0:4 offset1:36
	ds_read2_b32 v[28:29], v6 offset0:69 offset1:101
	ds_read2_b32 v[30:31], v6 offset0:134 offset1:166
	ds_read2_b32 v[32:33], v6 offset0:199 offset1:231
	v_lshl_add_u64 v[34:35], v[4:5], 0, v[0:1]
	s_waitcnt lgkmcnt(6)
	v_cvt_pk_bf16_f32 v4, v8, v10
	v_or_b32_e32 v8, v23, v18
	v_ashrrev_i32_e32 v10, 31, v23
	v_mul_lo_u32 v10, v10, v22
	v_mad_u64_u32 v[36:37], s[4:5], v8, v22, 0
	v_add_u32_e32 v37, v37, v10
	s_waitcnt lgkmcnt(4)
	v_cvt_pk_bf16_f32 v5, v12, v24
	s_waitcnt lgkmcnt(2)
	v_cvt_pk_bf16_f32 v6, v26, v28
	s_waitcnt lgkmcnt(0)
	v_cvt_pk_bf16_f32 v7, v30, v32
	v_lshl_add_u64 v[36:37], v[36:37], 1, v[34:35]
	v_or_b32_e32 v8, v23, v20
	global_store_dwordx4 v[36:37], v[4:7], off
	s_add_i32 s3, s3, s16
	s_cmpk_lt_i32 s3, 0x940
	v_cvt_pk_bf16_f32 v4, v9, v11
	v_mad_u64_u32 v[8:9], s[4:5], v8, v22, 0
	v_add_u32_e32 v9, v9, v10
	v_cvt_pk_bf16_f32 v5, v13, v25
	v_cvt_pk_bf16_f32 v6, v27, v29
	v_cvt_pk_bf16_f32 v7, v31, v33
	v_lshl_add_u64 v[8:9], v[8:9], 1, v[34:35]
	global_store_dwordx4 v[8:9], v[4:7], off
	s_cbranch_scc0 .Ltr1_75

.LBB0_362:
	s_cmp_lt_u32 s2, 128
	s_cbranch_scc1 .Ltr2_skip
	s_sub_u32 s3, s2, 128
	s_lshl_b32 s3, s3, 1
	s_addk_i32 s3, 0x940
	s_cmpk_gt_i32 s3, 0xd3f
	s_cbranch_scc1 .Ltr2_75
	s_load_dwordx4 s[84:87], s[0:1], 0x100
	s_load_dwordx4 s[88:91], s[0:1], 0xc8
	s_waitcnt lgkmcnt(0)
	s_barrier
	v_lshlrev_b32_e32 v0, 3, v129
	v_lshrrev_b32_e32 v14, 8, v129
	v_and_b32_e32 v0, 56, v0
	v_bfe_u32 v18, v129, 3, 5
	v_lshl_add_u32 v2, v14, 15, 0
	v_and_b32_e32 v15, 63, v129
	v_and_b32_e32 v3, 16, v129
	v_mul_u32_u24_e32 v5, 0x104, v0
	v_lshlrev_b32_e32 v6, 2, v18
	v_bfe_u32 v16, v129, 6, 2
	v_lshl_add_u32 v4, v15, 2, v2
	v_add3_u32 v19, v2, v5, v6
	v_mov_b32_e32 v2, s91
	v_mov_b32_e32 v6, s89
	v_cmp_eq_u32_e32 vcc, 0, v3
	v_mul_u32_u24_e32 v5, 0x104, v16
	v_and_b32_e32 v17, 15, v129
	v_cndmask_b32_e32 v3, v2, v6, vcc
	v_mov_b32_e32 v2, s90
	v_mov_b32_e32 v6, s88
	v_mov_b32_e32 v1, 0
	s_waitcnt lgkmcnt(0)
	s_movk_i32 s16, 0x100
	v_or_b32_e32 v20, 32, v18
	v_cndmask_b32_e32 v2, v2, v6, vcc
	v_add_u32_e32 v21, v4, v5
	v_lshlrev_b32_e32 v0, 1, v0
	s_branch .Ltr2_21
